# g3addr + strategy 2 (epilogue de-serialisation): attention pass-1 epilogue issues the 4 gsub loads together and all 16 scratch loads up front into dead registers (was 4 serial dword round trips + 4 ex
# speedup vs baseline: 1.0016x; 1.0005x over previous
; __device__ __forceinline__ unsigned cvtpk(float lo, float hi) { unsigned r; asm volatile("v_cvt_pk_bf16_f32 %0, %1, %2" : "=v"(r) : "v"(lo), "v"(hi)); return r; }
; template <bool GRPB> __device__ __forceinline__ void attn_pass(const float mbK, const float bmax2, const int pass, float* __restrict__ scr, bf16* __restrict__ mixrow, const float lam, const float* __restrict__ gsub, const float one_m_li, ...
;     ...
;     float g[4];
;     const float lam_ = *(const float*)(lds + 147328), oml_ = *(const float*)(lds + 147332);
; #pragma unroll
;     for (int d0 = 0; d0 < 4; ++d0) g[d0] = gsub[d0 * 32 + r32] * oml_;
; #pragma unroll
;     for (int r4 = 0; r4 < 4; ++r4) { const f32x4 lv = *(const f32x4*)(li_e + 8 * r4 + 4 * hi);
;       f32x4 av[4];
; #pragma unroll
;       for (int d0 = 0; d0 < 4; ++d0) av[d0] = scr4[d0 * 4 + r4];
; #pragma unroll
;       for (int i = 0; i < 4; ++i) { const float rl = __builtin_amdgcn_rcpf(lv[i]) * lam_; float dv[4]; float sq = 0.f;
; #pragma unroll
;         for (int d0 = 0; d0 < 4; ++d0) { dv[d0] = av[d0][i] - rl * o[d0][4 * r4 + i]; sq += dv[d0] * dv[d0]; }
;         sq += __shfl_xor(sq, 1); sq += __shfl_xor(sq, 2); sq += __shfl_xor(sq, 4); sq += __shfl_xor(sq, 8); sq += __shfl_xor(sq, 16);
;         const float rs = __builtin_amdgcn_rsqf(sq * (1.0f / 128.0f) + EPS);
;         unsigned short* orow = (unsigned short*)(ost_e + (8 * r4 + 4 * hi + i) * OST_PITCH) + r32;
; #pragma unroll
;         for (int d0 = 0; d0 < 4; ++d0) orow[d0 * 32] = (unsigned short)(cvtpk(dv[d0] * rs * g[d0], 0.f) & 0xffffu); } }
.LBB0_248:
	s_or_b64 exec, exec, s[0:1]
	v_lshrrev_b32_e32 v64, 6, v67
	s_movk_i32 s0, 0x2200
	v_mul_lo_u32 v88, v64, s0
	v_readlane_b32 s0, v254, 41
	v_ashrrev_i32_e32 v147, 31, v146
	v_lshlrev_b64 v[64:65], 8, v[146:147]
	v_add_u32_e32 v93, s0, v88
	v_readlane_b32 s0, v254, 37
	s_waitcnt lgkmcnt(0)
	v_lshl_add_u64 v[86:87], s[40:41], 0, v[64:65]
	v_add_u32_e32 v92, v66, v180
	v_mov_b32_e32 v64, s0
	ds_read_b64 v[84:85], v64
	ds_read_b128 v[80:83], v92
	v_lshlrev_b32_e32 v64, 2, v181
	global_load_dword v168, v64, s[42:43]
	global_load_dword v169, v64, s[42:43] offset:128
	global_load_dword v170, v64, s[42:43] offset:256
	global_load_dword v171, v64, s[42:43] offset:384
	v_lshlrev_b32_e32 v94, 1, v181
	s_waitcnt lgkmcnt(0)
	v_rcp_f32_e32 v80, v80
	s_nop 0
	v_mul_f32_e32 v80, v84, v80
	s_waitcnt vmcnt(0)
	v_mul_f32_e32 v89, v85, v168
	v_mul_f32_e32 v90, v85, v169
	v_mul_f32_e32 v91, v85, v170
	v_mul_f32_e32 v85, v85, v171
	global_load_dwordx4 v[76:79], v[86:87], off
	global_load_dwordx4 v[72:75], v[86:87], off offset:64
	global_load_dwordx4 v[68:71], v[86:87], off offset:128
	global_load_dwordx4 v[64:67], v[86:87], off offset:192
	global_load_dwordx4 v[96:99], v[86:87], off offset:16
	global_load_dwordx4 v[100:103], v[86:87], off offset:80
	global_load_dwordx4 v[104:107], v[86:87], off offset:144
	global_load_dwordx4 v[108:111], v[86:87], off offset:208
	global_load_dwordx4 v[112:115], v[86:87], off offset:32
	global_load_dwordx4 v[116:119], v[86:87], off offset:96
	global_load_dwordx4 v[120:123], v[86:87], off offset:160
	global_load_dwordx4 v[124:127], v[86:87], off offset:224
	global_load_dwordx4 v[128:131], v[86:87], off offset:48
	global_load_dwordx4 v[132:135], v[86:87], off offset:112
	global_load_dwordx4 v[136:139], v[86:87], off offset:176
	global_load_dwordx4 v[140:143], v[86:87], off offset:240
	s_waitcnt vmcnt(15)
	v_fma_f32 v0, -v0, v80, v76
	s_waitcnt vmcnt(14)
	v_fma_f32 v16, -v16, v80, v72
	v_mul_f32_e32 v72, v16, v16
	v_fmac_f32_e32 v72, v0, v0
	s_waitcnt vmcnt(13)
	v_fma_f32 v32, -v32, v80, v68
	v_fmac_f32_e32 v72, v32, v32
	s_waitcnt vmcnt(12)
	v_fma_f32 v48, -v48, v80, v64
	v_fmac_f32_e32 v72, v48, v48
	ds_bpermute_b32 v64, v145, v72
	s_waitcnt lgkmcnt(0)
	v_add_f32_e32 v64, v72, v64
	ds_bpermute_b32 v68, v210, v64
	s_waitcnt lgkmcnt(0)
	v_add_f32_e32 v64, v64, v68
	ds_bpermute_b32 v68, v211, v64
	s_waitcnt lgkmcnt(0)
	v_add_f32_e32 v64, v64, v68
	ds_bpermute_b32 v68, v212, v64
	s_waitcnt lgkmcnt(0)
	v_add_f32_e32 v64, v64, v68
	ds_bpermute_b32 v68, v213, v64
	s_waitcnt lgkmcnt(0)
	v_add_f32_e32 v64, v64, v68
	v_fmamk_f32 v64, v64, 0x3c000000, v233
	v_rsq_f32_e32 v64, v64
	v_mul_u32_u24_e32 v68, 0x440, v190
	v_add3_u32 v68, v93, v94, v68
	v_mul_f32_e32 v0, v0, v64
	v_mul_f32_e32 v0, v89, v0
	v_cvt_pk_bf16_f32 v0, v0, v144
	ds_write_b16 v68, v0
	v_mul_f32_e32 v0, v16, v64
	v_mul_f32_e32 v0, v90, v0
	v_cvt_pk_bf16_f32 v0, v0, v144
	ds_write_b16 v68, v0 offset:64
	v_mul_f32_e32 v0, v32, v64
	v_mul_f32_e32 v0, v91, v0
	v_cvt_pk_bf16_f32 v0, v0, v144
	ds_write_b16 v68, v0 offset:128
	v_mul_f32_e32 v0, v48, v64
	v_mul_f32_e32 v0, v85, v0
	v_cvt_pk_bf16_f32 v0, v0, v144
	ds_write_b16 v68, v0 offset:192
	v_rcp_f32_e32 v0, v81
	s_nop 0
	v_mul_f32_e32 v0, v84, v0
	v_fma_f32 v16, -v17, v0, v73
	v_fma_f32 v1, -v1, v0, v77
	v_mul_f32_e32 v17, v16, v16
	v_fmac_f32_e32 v17, v1, v1
	v_fma_f32 v32, -v33, v0, v69
	v_fmac_f32_e32 v17, v32, v32
	v_fma_f32 v0, -v49, v0, v65
	v_fmac_f32_e32 v17, v0, v0
	ds_bpermute_b32 v33, v145, v17
	s_waitcnt lgkmcnt(0)
	v_add_f32_e32 v17, v17, v33
	ds_bpermute_b32 v33, v210, v17
	s_waitcnt lgkmcnt(0)
	v_add_f32_e32 v17, v17, v33
	ds_bpermute_b32 v33, v211, v17
	s_waitcnt lgkmcnt(0)
	v_add_f32_e32 v17, v17, v33
	ds_bpermute_b32 v33, v212, v17
	s_waitcnt lgkmcnt(0)
	v_add_f32_e32 v17, v17, v33
	ds_bpermute_b32 v33, v213, v17
	s_waitcnt lgkmcnt(0)
	v_add_f32_e32 v17, v17, v33
	v_fmamk_f32 v17, v17, 0x3c000000, v233
	v_rsq_f32_e32 v17, v17
	s_nop 0
	v_mul_f32_e32 v1, v1, v17
	v_mul_f32_e32 v1, v89, v1
	v_cvt_pk_bf16_f32 v1, v1, v144
	ds_write_b16 v68, v1 offset:272
	v_mul_f32_e32 v1, v16, v17
	v_mul_f32_e32 v1, v90, v1
	v_cvt_pk_bf16_f32 v1, v1, v144
	ds_write_b16 v68, v1 offset:336
	v_mul_f32_e32 v1, v32, v17
	v_mul_f32_e32 v0, v0, v17
	v_mul_f32_e32 v1, v91, v1
	v_mul_f32_e32 v0, v85, v0
	v_cvt_pk_bf16_f32 v1, v1, v144
	ds_write_b16 v68, v1 offset:400
	v_cvt_pk_bf16_f32 v0, v0, v144
	ds_write_b16 v68, v0 offset:464
	v_rcp_f32_e32 v0, v82
	s_nop 0
	v_mul_f32_e32 v0, v84, v0
	v_fma_f32 v1, -v2, v0, v78
	v_fma_f32 v2, -v18, v0, v74
	v_mul_f32_e32 v16, v2, v2
	v_fmac_f32_e32 v16, v1, v1
	v_fma_f32 v17, -v34, v0, v70
	v_fmac_f32_e32 v16, v17, v17
	v_fma_f32 v0, -v50, v0, v66
	v_fmac_f32_e32 v16, v0, v0
	ds_bpermute_b32 v18, v145, v16
	s_waitcnt lgkmcnt(0)
	v_add_f32_e32 v16, v16, v18
	ds_bpermute_b32 v18, v210, v16
	s_waitcnt lgkmcnt(0)
	v_add_f32_e32 v16, v16, v18
	ds_bpermute_b32 v18, v211, v16
	s_waitcnt lgkmcnt(0)
	v_add_f32_e32 v16, v16, v18
	ds_bpermute_b32 v18, v212, v16
	s_waitcnt lgkmcnt(0)
	v_add_f32_e32 v16, v16, v18
	ds_bpermute_b32 v18, v213, v16
	s_waitcnt lgkmcnt(0)
	v_add_f32_e32 v16, v16, v18
	v_fmamk_f32 v16, v16, 0x3c000000, v233
	v_rsq_f32_e32 v16, v16
	s_nop 0
	v_mul_f32_e32 v1, v1, v16
	v_mul_f32_e32 v1, v89, v1
	v_cvt_pk_bf16_f32 v1, v1, v144
	ds_write_b16 v68, v1 offset:544
	v_mul_f32_e32 v1, v2, v16
	v_mul_f32_e32 v1, v90, v1
	v_cvt_pk_bf16_f32 v1, v1, v144
	ds_write_b16 v68, v1 offset:608
	v_mul_f32_e32 v1, v17, v16
	v_mul_f32_e32 v0, v0, v16
	v_mul_f32_e32 v1, v91, v1
	v_mul_f32_e32 v0, v85, v0
	v_cvt_pk_bf16_f32 v1, v1, v144
	ds_write_b16 v68, v1 offset:672
	v_cvt_pk_bf16_f32 v0, v0, v144
	ds_write_b16 v68, v0 offset:736
	v_rcp_f32_e32 v0, v83
	s_nop 0
	v_mul_f32_e32 v0, v84, v0
	v_fma_f32 v2, -v19, v0, v75
	v_fma_f32 v1, -v3, v0, v79
	v_mul_f32_e32 v3, v2, v2
	v_fmac_f32_e32 v3, v1, v1
	v_fma_f32 v16, -v35, v0, v71
	v_fmac_f32_e32 v3, v16, v16
	v_fma_f32 v0, -v51, v0, v67
	v_fmac_f32_e32 v3, v0, v0
	ds_bpermute_b32 v17, v145, v3
	s_waitcnt lgkmcnt(0)
; __device__ __forceinline__ unsigned cvtpk(float lo, float hi) { unsigned r; asm volatile("v_cvt_pk_bf16_f32 %0, %1, %2" : "=v"(r) : "v"(lo), "v"(hi)); return r; }
; template <bool GRPB> __device__ __forceinline__ void attn_pass(const float mbK, const float bmax2, const int pass, float* __restrict__ scr, bf16* __restrict__ mixrow, const float lam, const float* __restrict__ gsub, const float one_m_li, ...
;     ...
;     for (int r4 = 0; r4 < 4; ++r4) { const f32x4 lv = *(const f32x4*)(li_e + 8 * r4 + 4 * hi);
;       f32x4 av[4];
; #pragma unroll
;       for (int d0 = 0; d0 < 4; ++d0) av[d0] = scr4[d0 * 4 + r4];
; #pragma unroll
;       for (int i = 0; i < 4; ++i) { const float rl = __builtin_amdgcn_rcpf(lv[i]) * lam_; float dv[4]; float sq = 0.f;
; #pragma unroll
;         for (int d0 = 0; d0 < 4; ++d0) { dv[d0] = av[d0][i] - rl * o[d0][4 * r4 + i]; sq += dv[d0] * dv[d0]; }
;         sq += __shfl_xor(sq, 1); sq += __shfl_xor(sq, 2); sq += __shfl_xor(sq, 4); sq += __shfl_xor(sq, 8); sq += __shfl_xor(sq, 16);
;         const float rs = __builtin_amdgcn_rsqf(sq * (1.0f / 128.0f) + EPS);
;         unsigned short* orow = (unsigned short*)(ost_e + (8 * r4 + 4 * hi + i) * OST_PITCH) + r32;
; #pragma unroll
;         for (int d0 = 0; d0 < 4; ++d0) orow[d0 * 32] = (unsigned short)(cvtpk(dv[d0] * rs * g[d0], 0.f) & 0xffffu); } }
	v_add_f32_e32 v3, v3, v17
	ds_bpermute_b32 v17, v210, v3
	s_waitcnt lgkmcnt(0)
	v_add_f32_e32 v3, v3, v17
	ds_bpermute_b32 v17, v211, v3
	s_waitcnt lgkmcnt(0)
	v_add_f32_e32 v3, v3, v17
	ds_bpermute_b32 v17, v212, v3
	s_waitcnt lgkmcnt(0)
	v_add_f32_e32 v3, v3, v17
	ds_bpermute_b32 v17, v213, v3
	s_waitcnt lgkmcnt(0)
	v_add_f32_e32 v3, v3, v17
	v_fmamk_f32 v3, v3, 0x3c000000, v233
	v_rsq_f32_e32 v3, v3
	s_nop 0
	v_mul_f32_e32 v1, v1, v3
	v_mul_f32_e32 v1, v89, v1
	v_cvt_pk_bf16_f32 v1, v1, v144
	ds_write_b16 v68, v1 offset:816
	v_mul_f32_e32 v1, v2, v3
	v_mul_f32_e32 v1, v90, v1
	v_cvt_pk_bf16_f32 v1, v1, v144
	ds_write_b16 v68, v1 offset:880
	v_mul_f32_e32 v1, v16, v3
	v_mul_f32_e32 v0, v0, v3
	v_mul_f32_e32 v1, v91, v1
	v_mul_f32_e32 v0, v85, v0
	v_cvt_pk_bf16_f32 v1, v1, v144
	ds_write_b16 v68, v1 offset:944
	v_cvt_pk_bf16_f32 v0, v0, v144
	ds_write_b16 v68, v0 offset:1008
	ds_read_b128 v[64:67], v92 offset:32
	s_waitcnt lgkmcnt(0)
	v_rcp_f32_e32 v64, v64
	s_nop 0
	v_mul_f32_e32 v64, v84, v64
	s_waitcnt vmcnt(11)
	v_fma_f32 v4, -v4, v64, v96
	s_waitcnt vmcnt(10)
	v_fma_f32 v20, -v20, v64, v100
	v_mul_f32_e32 v32, v20, v20
	v_fmac_f32_e32 v32, v4, v4
	s_waitcnt vmcnt(9)
	v_fma_f32 v16, -v36, v64, v104
	v_fmac_f32_e32 v32, v16, v16
	s_waitcnt vmcnt(8)
	v_fma_f32 v0, -v52, v64, v108
	v_fmac_f32_e32 v32, v0, v0
	ds_bpermute_b32 v36, v145, v32
	s_waitcnt lgkmcnt(0)
	v_add_f32_e32 v32, v32, v36
	ds_bpermute_b32 v36, v210, v32
	s_waitcnt lgkmcnt(0)
	v_add_f32_e32 v32, v32, v36
	ds_bpermute_b32 v36, v211, v32
	s_waitcnt lgkmcnt(0)
	v_add_f32_e32 v32, v32, v36
	ds_bpermute_b32 v36, v212, v32
	s_waitcnt lgkmcnt(0)
	v_add_f32_e32 v32, v32, v36
	ds_bpermute_b32 v36, v213, v32
	s_waitcnt lgkmcnt(0)
	v_add_f32_e32 v32, v32, v36
	v_fmamk_f32 v32, v32, 0x3c000000, v233
	v_rsq_f32_e32 v32, v32
	s_nop 0
	v_mul_f32_e32 v4, v4, v32
	v_mul_f32_e32 v4, v89, v4
	v_cvt_pk_bf16_f32 v4, v4, v144
	ds_write_b16 v68, v4 offset:2176
	v_mul_f32_e32 v4, v20, v32
	v_mul_f32_e32 v4, v90, v4
	v_cvt_pk_bf16_f32 v4, v4, v144
	ds_write_b16 v68, v4 offset:2240
	v_mul_f32_e32 v4, v16, v32
	v_mul_f32_e32 v0, v0, v32
	v_mul_f32_e32 v4, v91, v4
	v_mul_f32_e32 v0, v85, v0
	v_cvt_pk_bf16_f32 v4, v4, v144
	ds_write_b16 v68, v4 offset:2304
	v_cvt_pk_bf16_f32 v0, v0, v144
	ds_write_b16 v68, v0 offset:2368
	v_rcp_f32_e32 v0, v65
	s_nop 0
	v_mul_f32_e32 v0, v84, v0
	v_fma_f32 v4, -v5, v0, v97
	v_fma_f32 v5, -v21, v0, v101
	v_mul_f32_e32 v16, v5, v5
	v_fmac_f32_e32 v16, v4, v4
	v_fma_f32 v17, -v37, v0, v105
	v_fmac_f32_e32 v16, v17, v17
	v_fma_f32 v0, -v53, v0, v109
	v_fmac_f32_e32 v16, v0, v0
	ds_bpermute_b32 v1, v145, v16
	s_waitcnt lgkmcnt(0)
	v_add_f32_e32 v1, v16, v1
	ds_bpermute_b32 v16, v210, v1
	s_waitcnt lgkmcnt(0)
	v_add_f32_e32 v1, v1, v16
	ds_bpermute_b32 v16, v211, v1
	s_waitcnt lgkmcnt(0)
	v_add_f32_e32 v1, v1, v16
	ds_bpermute_b32 v16, v212, v1
	s_waitcnt lgkmcnt(0)
	v_add_f32_e32 v1, v1, v16
	ds_bpermute_b32 v16, v213, v1
	s_waitcnt lgkmcnt(0)
	v_add_f32_e32 v1, v1, v16
	v_fmamk_f32 v1, v1, 0x3c000000, v233
	v_rsq_f32_e32 v1, v1
	s_nop 0
	v_mul_f32_e32 v4, v4, v1
	v_mul_f32_e32 v4, v89, v4
	v_cvt_pk_bf16_f32 v4, v4, v144
	ds_write_b16 v68, v4 offset:2448
	v_mul_f32_e32 v4, v5, v1
	v_mul_f32_e32 v4, v90, v4
	v_cvt_pk_bf16_f32 v4, v4, v144
	ds_write_b16 v68, v4 offset:2512
	v_mul_f32_e32 v4, v17, v1
	v_mul_f32_e32 v0, v0, v1
	v_mul_f32_e32 v4, v91, v4
	v_mul_f32_e32 v0, v85, v0
	v_cvt_pk_bf16_f32 v4, v4, v144
	ds_write_b16 v68, v4 offset:2576
	v_cvt_pk_bf16_f32 v0, v0, v144
	ds_write_b16 v68, v0 offset:2640
	v_rcp_f32_e32 v0, v66
	s_nop 0
	v_mul_f32_e32 v0, v84, v0
	v_fma_f32 v4, -v22, v0, v102
	v_fma_f32 v1, -v6, v0, v98
	v_mul_f32_e32 v5, v4, v4
	v_fmac_f32_e32 v5, v1, v1
	v_fma_f32 v6, -v38, v0, v106
	v_fmac_f32_e32 v5, v6, v6
	v_fma_f32 v0, -v54, v0, v110
	v_fmac_f32_e32 v5, v0, v0
	ds_bpermute_b32 v2, v145, v5
	s_waitcnt lgkmcnt(0)
	v_add_f32_e32 v2, v5, v2
	ds_bpermute_b32 v5, v210, v2
	s_waitcnt lgkmcnt(0)
	v_add_f32_e32 v2, v2, v5
	ds_bpermute_b32 v5, v211, v2
	s_waitcnt lgkmcnt(0)
	v_add_f32_e32 v2, v2, v5
	ds_bpermute_b32 v5, v212, v2
	s_waitcnt lgkmcnt(0)
	v_add_f32_e32 v2, v2, v5
	ds_bpermute_b32 v5, v213, v2
	s_waitcnt lgkmcnt(0)
	v_add_f32_e32 v2, v2, v5
	v_fmamk_f32 v2, v2, 0x3c000000, v233
	v_rsq_f32_e32 v2, v2
	s_nop 0
	v_mul_f32_e32 v1, v1, v2
	v_mul_f32_e32 v1, v89, v1
	v_cvt_pk_bf16_f32 v1, v1, v144
	ds_write_b16 v68, v1 offset:2720
	v_mul_f32_e32 v1, v4, v2
	v_mul_f32_e32 v1, v90, v1
	v_cvt_pk_bf16_f32 v1, v1, v144
	ds_write_b16 v68, v1 offset:2784
	v_mul_f32_e32 v1, v6, v2
	v_mul_f32_e32 v0, v0, v2
	v_mul_f32_e32 v1, v91, v1
	v_mul_f32_e32 v0, v85, v0
	v_cvt_pk_bf16_f32 v1, v1, v144
	ds_write_b16 v68, v1 offset:2848
	v_cvt_pk_bf16_f32 v0, v0, v144
	ds_write_b16 v68, v0 offset:2912
	v_rcp_f32_e32 v0, v67
	s_nop 0
	v_mul_f32_e32 v0, v84, v0
	v_fma_f32 v2, -v23, v0, v103
	v_fma_f32 v1, -v7, v0, v99
	v_mul_f32_e32 v4, v2, v2
	v_fmac_f32_e32 v4, v1, v1
	v_fma_f32 v5, -v39, v0, v107
	v_fmac_f32_e32 v4, v5, v5
	v_fma_f32 v0, -v55, v0, v111
	v_fmac_f32_e32 v4, v0, v0
	ds_bpermute_b32 v3, v145, v4
	s_waitcnt lgkmcnt(0)
	v_add_f32_e32 v3, v4, v3
	ds_bpermute_b32 v4, v210, v3
	s_waitcnt lgkmcnt(0)
	v_add_f32_e32 v3, v3, v4
	ds_bpermute_b32 v4, v211, v3
	s_waitcnt lgkmcnt(0)
	v_add_f32_e32 v3, v3, v4
	ds_bpermute_b32 v4, v212, v3
	s_waitcnt lgkmcnt(0)
	v_add_f32_e32 v3, v3, v4
	ds_bpermute_b32 v4, v213, v3
	s_waitcnt lgkmcnt(0)
; __device__ __forceinline__ unsigned cvtpk(float lo, float hi) { unsigned r; asm volatile("v_cvt_pk_bf16_f32 %0, %1, %2" : "=v"(r) : "v"(lo), "v"(hi)); return r; }
; template <bool GRPB> __device__ __forceinline__ void attn_pass(const float mbK, const float bmax2, const int pass, float* __restrict__ scr, bf16* __restrict__ mixrow, const float lam, const float* __restrict__ gsub, const float one_m_li, ...
;     ...
;     for (int r4 = 0; r4 < 4; ++r4) { const f32x4 lv = *(const f32x4*)(li_e + 8 * r4 + 4 * hi);
;       f32x4 av[4];
; #pragma unroll
;       for (int d0 = 0; d0 < 4; ++d0) av[d0] = scr4[d0 * 4 + r4];
; #pragma unroll
;       for (int i = 0; i < 4; ++i) { const float rl = __builtin_amdgcn_rcpf(lv[i]) * lam_; float dv[4]; float sq = 0.f;
; #pragma unroll
;         for (int d0 = 0; d0 < 4; ++d0) { dv[d0] = av[d0][i] - rl * o[d0][4 * r4 + i]; sq += dv[d0] * dv[d0]; }
;         sq += __shfl_xor(sq, 1); sq += __shfl_xor(sq, 2); sq += __shfl_xor(sq, 4); sq += __shfl_xor(sq, 8); sq += __shfl_xor(sq, 16);
;         const float rs = __builtin_amdgcn_rsqf(sq * (1.0f / 128.0f) + EPS);
;         unsigned short* orow = (unsigned short*)(ost_e + (8 * r4 + 4 * hi + i) * OST_PITCH) + r32;
; #pragma unroll
;         for (int d0 = 0; d0 < 4; ++d0) orow[d0 * 32] = (unsigned short)(cvtpk(dv[d0] * rs * g[d0], 0.f) & 0xffffu); } }
	v_add_f32_e32 v3, v3, v4
	v_fmamk_f32 v3, v3, 0x3c000000, v233
	v_rsq_f32_e32 v3, v3
	s_nop 0
	v_mul_f32_e32 v1, v1, v3
	v_mul_f32_e32 v1, v89, v1
	v_cvt_pk_bf16_f32 v1, v1, v144
	ds_write_b16 v68, v1 offset:2992
	v_mul_f32_e32 v1, v2, v3
	v_mul_f32_e32 v1, v90, v1
	v_cvt_pk_bf16_f32 v1, v1, v144
	ds_write_b16 v68, v1 offset:3056
	v_mul_f32_e32 v1, v5, v3
	v_mul_f32_e32 v0, v0, v3
	v_mul_f32_e32 v1, v91, v1
	v_mul_f32_e32 v0, v85, v0
	v_cvt_pk_bf16_f32 v1, v1, v144
	ds_write_b16 v68, v1 offset:3120
	v_cvt_pk_bf16_f32 v0, v0, v144
	ds_write_b16 v68, v0 offset:3184
	ds_read_b128 v[32:35], v92 offset:64
	s_waitcnt lgkmcnt(0)
	v_rcp_f32_e32 v32, v32
	s_nop 0
	v_mul_f32_e32 v32, v84, v32
	s_waitcnt vmcnt(7)
	v_fma_f32 v8, -v8, v32, v112
	s_waitcnt vmcnt(6)
	v_fma_f32 v16, -v24, v32, v116
	v_mul_f32_e32 v20, v16, v16
	v_fmac_f32_e32 v20, v8, v8
	s_waitcnt vmcnt(5)
	v_fma_f32 v4, -v40, v32, v120
	v_fmac_f32_e32 v20, v4, v4
	s_waitcnt vmcnt(4)
	v_fma_f32 v0, -v56, v32, v124
	v_fmac_f32_e32 v20, v0, v0
	ds_bpermute_b32 v24, v145, v20
	s_waitcnt lgkmcnt(0)
	v_add_f32_e32 v20, v20, v24
	ds_bpermute_b32 v24, v210, v20
	s_waitcnt lgkmcnt(0)
	v_add_f32_e32 v20, v20, v24
	ds_bpermute_b32 v24, v211, v20
	s_waitcnt lgkmcnt(0)
	v_add_f32_e32 v20, v20, v24
	ds_bpermute_b32 v24, v212, v20
	s_waitcnt lgkmcnt(0)
	v_add_f32_e32 v20, v20, v24
	ds_bpermute_b32 v24, v213, v20
	s_waitcnt lgkmcnt(0)
	v_add_f32_e32 v20, v20, v24
	v_fmamk_f32 v20, v20, 0x3c000000, v233
	v_rsq_f32_e32 v20, v20
	s_nop 0
	v_mul_f32_e32 v8, v8, v20
	v_mul_f32_e32 v8, v89, v8
	v_cvt_pk_bf16_f32 v8, v8, v144
	ds_write_b16 v68, v8 offset:4352
	v_mul_f32_e32 v8, v16, v20
	v_mul_f32_e32 v4, v4, v20
	v_mul_f32_e32 v0, v0, v20
	v_mul_f32_e32 v8, v90, v8
	v_mul_f32_e32 v4, v91, v4
	v_mul_f32_e32 v0, v85, v0
	v_cvt_pk_bf16_f32 v8, v8, v144
	ds_write_b16 v68, v8 offset:4416
	v_cvt_pk_bf16_f32 v4, v4, v144
	ds_write_b16 v68, v4 offset:4480
	v_cvt_pk_bf16_f32 v0, v0, v144
	ds_write_b16 v68, v0 offset:4544
	v_rcp_f32_e32 v0, v33
	s_nop 0
	v_mul_f32_e32 v0, v84, v0
	v_fma_f32 v8, -v25, v0, v117
	v_fma_f32 v4, -v9, v0, v113
	v_mul_f32_e32 v9, v8, v8
	v_fmac_f32_e32 v9, v4, v4
	v_fma_f32 v5, -v41, v0, v121
	v_fmac_f32_e32 v9, v5, v5
	v_fma_f32 v0, -v57, v0, v125
	v_fmac_f32_e32 v9, v0, v0
	ds_bpermute_b32 v1, v145, v9
	s_waitcnt lgkmcnt(0)
	v_add_f32_e32 v1, v9, v1
	ds_bpermute_b32 v9, v210, v1
	s_waitcnt lgkmcnt(0)
	v_add_f32_e32 v1, v1, v9
	ds_bpermute_b32 v9, v211, v1
	s_waitcnt lgkmcnt(0)
	v_add_f32_e32 v1, v1, v9
	ds_bpermute_b32 v9, v212, v1
	s_waitcnt lgkmcnt(0)
	v_add_f32_e32 v1, v1, v9
	ds_bpermute_b32 v9, v213, v1
	s_waitcnt lgkmcnt(0)
	v_add_f32_e32 v1, v1, v9
	v_fmamk_f32 v1, v1, 0x3c000000, v233
	v_rsq_f32_e32 v1, v1
	s_nop 0
	v_mul_f32_e32 v4, v4, v1
	v_mul_f32_e32 v4, v89, v4
	v_cvt_pk_bf16_f32 v4, v4, v144
	ds_write_b16 v68, v4 offset:4624
	v_mul_f32_e32 v4, v8, v1
	v_mul_f32_e32 v4, v90, v4
	v_cvt_pk_bf16_f32 v4, v4, v144
	ds_write_b16 v68, v4 offset:4688
	v_mul_f32_e32 v4, v5, v1
	v_mul_f32_e32 v0, v0, v1
	v_mul_f32_e32 v4, v91, v4
	v_mul_f32_e32 v0, v85, v0
	v_cvt_pk_bf16_f32 v4, v4, v144
	ds_write_b16 v68, v4 offset:4752
	v_cvt_pk_bf16_f32 v0, v0, v144
	ds_write_b16 v68, v0 offset:4816
	v_rcp_f32_e32 v0, v34
	s_nop 0
	v_mul_f32_e32 v0, v84, v0
	v_fma_f32 v4, -v26, v0, v118
	v_fma_f32 v1, -v10, v0, v114
	v_mul_f32_e32 v5, v4, v4
	v_fmac_f32_e32 v5, v1, v1
	v_fma_f32 v6, -v42, v0, v122
	v_fmac_f32_e32 v5, v6, v6
	v_fma_f32 v0, -v58, v0, v126
	v_fmac_f32_e32 v5, v0, v0
	ds_bpermute_b32 v2, v145, v5
	s_waitcnt lgkmcnt(0)
	v_add_f32_e32 v2, v5, v2
	ds_bpermute_b32 v5, v210, v2
	s_waitcnt lgkmcnt(0)
	v_add_f32_e32 v2, v2, v5
	ds_bpermute_b32 v5, v211, v2
	s_waitcnt lgkmcnt(0)
	v_add_f32_e32 v2, v2, v5
	ds_bpermute_b32 v5, v212, v2
	s_waitcnt lgkmcnt(0)
	v_add_f32_e32 v2, v2, v5
	ds_bpermute_b32 v5, v213, v2
	s_waitcnt lgkmcnt(0)
	v_add_f32_e32 v2, v2, v5
	v_fmamk_f32 v2, v2, 0x3c000000, v233
	v_rsq_f32_e32 v2, v2
	s_nop 0
	v_mul_f32_e32 v1, v1, v2
	v_mul_f32_e32 v1, v89, v1
	v_cvt_pk_bf16_f32 v1, v1, v144
	ds_write_b16 v68, v1 offset:4896
	v_mul_f32_e32 v1, v4, v2
	v_mul_f32_e32 v1, v90, v1
	v_cvt_pk_bf16_f32 v1, v1, v144
	ds_write_b16 v68, v1 offset:4960
	v_mul_f32_e32 v1, v6, v2
	v_mul_f32_e32 v0, v0, v2
	v_mul_f32_e32 v1, v91, v1
	v_mul_f32_e32 v0, v85, v0
	v_cvt_pk_bf16_f32 v1, v1, v144
	ds_write_b16 v68, v1 offset:5024
	v_cvt_pk_bf16_f32 v0, v0, v144
	ds_write_b16 v68, v0 offset:5088
	v_rcp_f32_e32 v0, v35
	s_nop 0
	v_mul_f32_e32 v0, v84, v0
	v_fma_f32 v2, -v27, v0, v119
	v_fma_f32 v1, -v11, v0, v115
	v_mul_f32_e32 v4, v2, v2
	v_fmac_f32_e32 v4, v1, v1
	v_fma_f32 v5, -v43, v0, v123
	v_fmac_f32_e32 v4, v5, v5
	v_fma_f32 v0, -v59, v0, v127
	v_fmac_f32_e32 v4, v0, v0
	ds_bpermute_b32 v3, v145, v4
	s_waitcnt lgkmcnt(0)
	v_add_f32_e32 v3, v4, v3
	ds_bpermute_b32 v4, v210, v3
	s_waitcnt lgkmcnt(0)
	v_add_f32_e32 v3, v3, v4
	ds_bpermute_b32 v4, v211, v3
	s_waitcnt lgkmcnt(0)
	v_add_f32_e32 v3, v3, v4
	ds_bpermute_b32 v4, v212, v3
	s_waitcnt lgkmcnt(0)
	v_add_f32_e32 v3, v3, v4
	ds_bpermute_b32 v4, v213, v3
	s_waitcnt lgkmcnt(0)
; __device__ __forceinline__ unsigned cvtpk(float lo, float hi) { unsigned r; asm volatile("v_cvt_pk_bf16_f32 %0, %1, %2" : "=v"(r) : "v"(lo), "v"(hi)); return r; }
; template <bool GRPB> __device__ __forceinline__ void attn_pass(const float mbK, const float bmax2, const int pass, float* __restrict__ scr, bf16* __restrict__ mixrow, const float lam, const float* __restrict__ gsub, const float one_m_li, ...
;     ...
;     for (int r4 = 0; r4 < 4; ++r4) { const f32x4 lv = *(const f32x4*)(li_e + 8 * r4 + 4 * hi);
;       f32x4 av[4];
; #pragma unroll
;       for (int d0 = 0; d0 < 4; ++d0) av[d0] = scr4[d0 * 4 + r4];
; #pragma unroll
;       for (int i = 0; i < 4; ++i) { const float rl = __builtin_amdgcn_rcpf(lv[i]) * lam_; float dv[4]; float sq = 0.f;
; #pragma unroll
;         for (int d0 = 0; d0 < 4; ++d0) { dv[d0] = av[d0][i] - rl * o[d0][4 * r4 + i]; sq += dv[d0] * dv[d0]; }
;         sq += __shfl_xor(sq, 1); sq += __shfl_xor(sq, 2); sq += __shfl_xor(sq, 4); sq += __shfl_xor(sq, 8); sq += __shfl_xor(sq, 16);
;         const float rs = __builtin_amdgcn_rsqf(sq * (1.0f / 128.0f) + EPS);
;         unsigned short* orow = (unsigned short*)(ost_e + (8 * r4 + 4 * hi + i) * OST_PITCH) + r32;
; #pragma unroll
;         for (int d0 = 0; d0 < 4; ++d0) orow[d0 * 32] = (unsigned short)(cvtpk(dv[d0] * rs * g[d0], 0.f) & 0xffffu); } }
;     asm volatile("s_waitcnt lgkmcnt(0)" ::: "memory");
	v_add_f32_e32 v3, v3, v4
	v_fmamk_f32 v3, v3, 0x3c000000, v233
	v_rsq_f32_e32 v3, v3
	s_nop 0
	v_mul_f32_e32 v1, v1, v3
	v_mul_f32_e32 v1, v89, v1
	v_cvt_pk_bf16_f32 v1, v1, v144
	ds_write_b16 v68, v1 offset:5168
	v_mul_f32_e32 v1, v2, v3
	v_mul_f32_e32 v1, v90, v1
	v_cvt_pk_bf16_f32 v1, v1, v144
	ds_write_b16 v68, v1 offset:5232
	v_mul_f32_e32 v1, v5, v3
	v_mul_f32_e32 v0, v0, v3
	v_mul_f32_e32 v1, v91, v1
	v_mul_f32_e32 v0, v85, v0
	v_cvt_pk_bf16_f32 v1, v1, v144
	ds_write_b16 v68, v1 offset:5296
	v_cvt_pk_bf16_f32 v0, v0, v144
	ds_write_b16 v68, v0 offset:5360
	ds_read_b128 v[20:23], v92 offset:96
	s_waitcnt lgkmcnt(0)
	v_rcp_f32_e32 v20, v20
	s_nop 0
	v_mul_f32_e32 v20, v84, v20
	s_waitcnt vmcnt(3)
	v_fma_f32 v8, -v12, v20, v128
	s_waitcnt vmcnt(2)
	v_fma_f32 v12, -v28, v20, v132
	v_mul_f32_e32 v16, v12, v12
	v_fmac_f32_e32 v16, v8, v8
	s_waitcnt vmcnt(1)
	v_fma_f32 v4, -v44, v20, v136
	v_fmac_f32_e32 v16, v4, v4
	s_waitcnt vmcnt(0)
	v_fma_f32 v0, -v60, v20, v140
	v_fmac_f32_e32 v16, v0, v0
	ds_bpermute_b32 v20, v145, v16
	s_waitcnt lgkmcnt(0)
	v_add_f32_e32 v16, v16, v20
	ds_bpermute_b32 v20, v210, v16
	s_waitcnt lgkmcnt(0)
	v_add_f32_e32 v16, v16, v20
	ds_bpermute_b32 v20, v211, v16
	s_waitcnt lgkmcnt(0)
	v_add_f32_e32 v16, v16, v20
	ds_bpermute_b32 v20, v212, v16
	s_waitcnt lgkmcnt(0)
	v_add_f32_e32 v16, v16, v20
	ds_bpermute_b32 v20, v213, v16
	s_waitcnt lgkmcnt(0)
	v_add_f32_e32 v16, v16, v20
	v_fmamk_f32 v16, v16, 0x3c000000, v233
	v_rsq_f32_e32 v16, v16
	s_nop 0
	v_mul_f32_e32 v8, v8, v16
	v_mul_f32_e32 v8, v89, v8
	v_cvt_pk_bf16_f32 v8, v8, v144
	ds_write_b16 v68, v8 offset:6528
	v_mul_f32_e32 v8, v12, v16
	v_mul_f32_e32 v4, v4, v16
	v_mul_f32_e32 v0, v0, v16
	v_mul_f32_e32 v8, v90, v8
	v_mul_f32_e32 v4, v91, v4
	v_mul_f32_e32 v0, v85, v0
	v_cvt_pk_bf16_f32 v8, v8, v144
	ds_write_b16 v68, v8 offset:6592
	v_cvt_pk_bf16_f32 v4, v4, v144
	ds_write_b16 v68, v4 offset:6656
	v_cvt_pk_bf16_f32 v0, v0, v144
	ds_write_b16 v68, v0 offset:6720
	v_rcp_f32_e32 v0, v21
	s_nop 0
	v_mul_f32_e32 v0, v84, v0
	v_fma_f32 v8, -v29, v0, v133
	v_fma_f32 v4, -v13, v0, v129
	v_mul_f32_e32 v9, v8, v8
	v_fmac_f32_e32 v9, v4, v4
	v_fma_f32 v5, -v45, v0, v137
	v_fmac_f32_e32 v9, v5, v5
	v_fma_f32 v0, -v61, v0, v141
	v_fmac_f32_e32 v9, v0, v0
	ds_bpermute_b32 v1, v145, v9
	s_waitcnt lgkmcnt(0)
	v_add_f32_e32 v1, v9, v1
	ds_bpermute_b32 v9, v210, v1
	s_waitcnt lgkmcnt(0)
	v_add_f32_e32 v1, v1, v9
	ds_bpermute_b32 v9, v211, v1
	s_waitcnt lgkmcnt(0)
	v_add_f32_e32 v1, v1, v9
	ds_bpermute_b32 v9, v212, v1
	s_waitcnt lgkmcnt(0)
	v_add_f32_e32 v1, v1, v9
	ds_bpermute_b32 v9, v213, v1
	s_waitcnt lgkmcnt(0)
	v_add_f32_e32 v1, v1, v9
	v_fmamk_f32 v1, v1, 0x3c000000, v233
	v_rsq_f32_e32 v1, v1
	s_nop 0
	v_mul_f32_e32 v4, v4, v1
	v_mul_f32_e32 v4, v89, v4
	v_cvt_pk_bf16_f32 v4, v4, v144
	ds_write_b16 v68, v4 offset:6800
	v_mul_f32_e32 v4, v8, v1
	v_mul_f32_e32 v4, v90, v4
	v_cvt_pk_bf16_f32 v4, v4, v144
	ds_write_b16 v68, v4 offset:6864
	v_mul_f32_e32 v4, v5, v1
	v_mul_f32_e32 v0, v0, v1
	v_mul_f32_e32 v4, v91, v4
	v_mul_f32_e32 v0, v85, v0
	v_cvt_pk_bf16_f32 v4, v4, v144
	ds_write_b16 v68, v4 offset:6928
	v_cvt_pk_bf16_f32 v0, v0, v144
	ds_write_b16 v68, v0 offset:6992
	v_rcp_f32_e32 v0, v22
	s_nop 0
	v_mul_f32_e32 v0, v84, v0
	v_fma_f32 v4, -v30, v0, v134
	v_fma_f32 v1, -v14, v0, v130
	v_mul_f32_e32 v5, v4, v4
	v_fmac_f32_e32 v5, v1, v1
	v_fma_f32 v6, -v46, v0, v138
	v_fmac_f32_e32 v5, v6, v6
	v_fma_f32 v0, -v62, v0, v142
	v_fmac_f32_e32 v5, v0, v0
	ds_bpermute_b32 v2, v145, v5
	s_waitcnt lgkmcnt(0)
	v_add_f32_e32 v2, v5, v2
	ds_bpermute_b32 v5, v210, v2
	s_waitcnt lgkmcnt(0)
	v_add_f32_e32 v2, v2, v5
	ds_bpermute_b32 v5, v211, v2
	s_waitcnt lgkmcnt(0)
	v_add_f32_e32 v2, v2, v5
	ds_bpermute_b32 v5, v212, v2
	s_waitcnt lgkmcnt(0)
	v_add_f32_e32 v2, v2, v5
	ds_bpermute_b32 v5, v213, v2
	s_waitcnt lgkmcnt(0)
	v_add_f32_e32 v2, v2, v5
	v_fmamk_f32 v2, v2, 0x3c000000, v233
	v_rsq_f32_e32 v2, v2
	s_nop 0
	v_mul_f32_e32 v1, v1, v2
	v_mul_f32_e32 v1, v89, v1
	v_cvt_pk_bf16_f32 v1, v1, v144
	ds_write_b16 v68, v1 offset:7072
	v_mul_f32_e32 v1, v4, v2
	v_mul_f32_e32 v1, v90, v1
	v_cvt_pk_bf16_f32 v1, v1, v144
	ds_write_b16 v68, v1 offset:7136
	v_mul_f32_e32 v1, v6, v2
	v_mul_f32_e32 v0, v0, v2
	v_mul_f32_e32 v1, v91, v1
	v_mul_f32_e32 v0, v85, v0
	v_cvt_pk_bf16_f32 v1, v1, v144
	ds_write_b16 v68, v1 offset:7200
	v_cvt_pk_bf16_f32 v0, v0, v144
	ds_write_b16 v68, v0 offset:7264
	v_rcp_f32_e32 v0, v23
	s_nop 0
	v_mul_f32_e32 v0, v84, v0
	v_fma_f32 v2, -v31, v0, v135
	v_fma_f32 v1, -v15, v0, v131
	v_mul_f32_e32 v4, v2, v2
	v_fmac_f32_e32 v4, v1, v1
	v_fma_f32 v5, -v47, v0, v139
	v_fmac_f32_e32 v4, v5, v5
	v_fma_f32 v0, -v63, v0, v143
	v_fmac_f32_e32 v4, v0, v0
	ds_bpermute_b32 v3, v145, v4
	s_waitcnt lgkmcnt(0)
	v_add_f32_e32 v3, v4, v3
	ds_bpermute_b32 v4, v210, v3
	s_waitcnt lgkmcnt(0)
	v_add_f32_e32 v3, v3, v4
	ds_bpermute_b32 v4, v211, v3
	s_waitcnt lgkmcnt(0)
	v_add_f32_e32 v3, v3, v4
	ds_bpermute_b32 v4, v212, v3
	s_waitcnt lgkmcnt(0)
	v_add_f32_e32 v3, v3, v4
	ds_bpermute_b32 v4, v213, v3
	s_waitcnt lgkmcnt(0)
	v_add_f32_e32 v3, v3, v4
	v_fmamk_f32 v3, v3, 0x3c000000, v233
	v_rsq_f32_e32 v3, v3
	s_nop 0
	v_mul_f32_e32 v1, v1, v3
	v_mul_f32_e32 v1, v89, v1
	v_cvt_pk_bf16_f32 v1, v1, v144
	ds_write_b16 v68, v1 offset:7344
	v_mul_f32_e32 v1, v2, v3
	v_mul_f32_e32 v1, v90, v1
	v_cvt_pk_bf16_f32 v1, v1, v144
	ds_write_b16 v68, v1 offset:7408
	v_mul_f32_e32 v1, v5, v3
	v_mul_f32_e32 v0, v0, v3
	v_mul_f32_e32 v1, v91, v1
	v_mul_f32_e32 v0, v85, v0
	v_cvt_pk_bf16_f32 v1, v1, v144
	ds_write_b16 v68, v1 offset:7472
	v_cvt_pk_bf16_f32 v0, v0, v144
	ds_write_b16 v68, v0 offset:7536
	s_waitcnt lgkmcnt(0)

; __device__ __forceinline__ unsigned cvtpk(float lo, float hi) { unsigned r; asm volatile("v_cvt_pk_bf16_f32 %0, %1, %2" : "=v"(r) : "v"(lo), "v"(hi)); return r; }
; template <bool GRPB> __device__ __forceinline__ void attn_pass(const float mbK, const float bmax2, const int pass, float* __restrict__ scr, bf16* __restrict__ mixrow, const float lam, const float* __restrict__ gsub, const float one_m_li, ...
;     ...
;     float g[4];
;     const float lam_ = *(const float*)(lds + 147328), oml_ = *(const float*)(lds + 147332);
; #pragma unroll
;     for (int d0 = 0; d0 < 4; ++d0) g[d0] = gsub[d0 * 32 + r32] * oml_;
; #pragma unroll
;     for (int r4 = 0; r4 < 4; ++r4) { const f32x4 lv = *(const f32x4*)(li_e + 8 * r4 + 4 * hi);
;       f32x4 av[4];
; #pragma unroll
;       for (int d0 = 0; d0 < 4; ++d0) av[d0] = scr4[d0 * 4 + r4];
; #pragma unroll
;       for (int i = 0; i < 4; ++i) { const float rl = __builtin_amdgcn_rcpf(lv[i]) * lam_; float dv[4]; float sq = 0.f;
; #pragma unroll
;         for (int d0 = 0; d0 < 4; ++d0) { dv[d0] = av[d0][i] - rl * o[d0][4 * r4 + i]; sq += dv[d0] * dv[d0]; }
;         sq += __shfl_xor(sq, 1); sq += __shfl_xor(sq, 2); sq += __shfl_xor(sq, 4); sq += __shfl_xor(sq, 8); sq += __shfl_xor(sq, 16);
;         const float rs = __builtin_amdgcn_rsqf(sq * (1.0f / 128.0f) + EPS);
;         unsigned short* orow = (unsigned short*)(ost_e + (8 * r4 + 4 * hi + i) * OST_PITCH) + r32;
; #pragma unroll
;         for (int d0 = 0; d0 < 4; ++d0) orow[d0 * 32] = (unsigned short)(cvtpk(dv[d0] * rs * g[d0], 0.f) & 0xffffu); } }
.LBB0_346:
	s_or_b64 exec, exec, s[0:1]
	v_lshrrev_b32_e32 v64, 6, v67
	s_movk_i32 s0, 0x2200
	v_mul_lo_u32 v88, v64, s0
	v_readlane_b32 s0, v254, 41
	v_ashrrev_i32_e32 v147, 31, v146
	v_lshlrev_b64 v[64:65], 8, v[146:147]
	v_add_u32_e32 v93, s0, v88
	v_readlane_b32 s0, v254, 37
	s_waitcnt lgkmcnt(0)
	v_lshl_add_u64 v[86:87], s[40:41], 0, v[64:65]
	v_add_u32_e32 v92, v66, v200
	v_mov_b32_e32 v64, s0
	ds_read_b64 v[84:85], v64
	ds_read_b128 v[80:83], v92
	v_lshlrev_b32_e32 v64, 2, v218
	global_load_dword v168, v64, s[42:43]
	global_load_dword v169, v64, s[42:43] offset:128
	global_load_dword v170, v64, s[42:43] offset:256
	global_load_dword v171, v64, s[42:43] offset:384
	v_lshlrev_b32_e32 v94, 1, v218
	s_mov_b64 s[0:1], 0
	s_waitcnt lgkmcnt(0)
	v_rcp_f32_e32 v80, v80
	s_waitcnt vmcnt(0)
	v_mul_f32_e32 v89, v85, v168
	v_mul_f32_e32 v80, v84, v80
	v_mul_f32_e32 v90, v85, v169
	v_mul_f32_e32 v91, v85, v170
	v_mul_f32_e32 v85, v85, v171
	global_load_dwordx4 v[76:79], v[86:87], off
	global_load_dwordx4 v[72:75], v[86:87], off offset:64
	global_load_dwordx4 v[68:71], v[86:87], off offset:128
	global_load_dwordx4 v[64:67], v[86:87], off offset:192
	global_load_dwordx4 v[96:99], v[86:87], off offset:16
	global_load_dwordx4 v[100:103], v[86:87], off offset:80
	global_load_dwordx4 v[104:107], v[86:87], off offset:144
	global_load_dwordx4 v[108:111], v[86:87], off offset:208
	global_load_dwordx4 v[112:115], v[86:87], off offset:32
	global_load_dwordx4 v[116:119], v[86:87], off offset:96
	global_load_dwordx4 v[120:123], v[86:87], off offset:160
	global_load_dwordx4 v[124:127], v[86:87], off offset:224
	global_load_dwordx4 v[128:131], v[86:87], off offset:48
	global_load_dwordx4 v[132:135], v[86:87], off offset:112
	global_load_dwordx4 v[136:139], v[86:87], off offset:176
	global_load_dwordx4 v[140:143], v[86:87], off offset:240
	s_waitcnt vmcnt(15)
	v_fma_f32 v0, -v0, v80, v76
	s_waitcnt vmcnt(14)
	v_fma_f32 v16, -v16, v80, v72
	v_mul_f32_e32 v72, v16, v16
	v_fmac_f32_e32 v72, v0, v0
	s_waitcnt vmcnt(13)
	v_fma_f32 v32, -v32, v80, v68
	v_fmac_f32_e32 v72, v32, v32
	s_waitcnt vmcnt(12)
	v_fma_f32 v48, -v48, v80, v64
	v_fmac_f32_e32 v72, v48, v48
	ds_bpermute_b32 v64, v145, v72
	s_waitcnt lgkmcnt(0)
	v_add_f32_e32 v64, v72, v64
	ds_bpermute_b32 v68, v210, v64
	s_waitcnt lgkmcnt(0)
	v_add_f32_e32 v64, v64, v68
	ds_bpermute_b32 v68, v211, v64
	s_waitcnt lgkmcnt(0)
	v_add_f32_e32 v64, v64, v68
	ds_bpermute_b32 v68, v212, v64
	s_waitcnt lgkmcnt(0)
	v_add_f32_e32 v64, v64, v68
	ds_bpermute_b32 v68, v213, v64
	s_waitcnt lgkmcnt(0)
	v_add_f32_e32 v64, v64, v68
	v_fmamk_f32 v64, v64, 0x3c000000, v233
	v_rsq_f32_e32 v64, v64
	v_mul_u32_u24_e32 v68, 0x440, v217
	v_add3_u32 v68, v93, v94, v68
	v_mul_f32_e32 v0, v0, v64
	v_mul_f32_e32 v0, v89, v0
	v_cvt_pk_bf16_f32 v0, v0, v144
	ds_write_b16 v68, v0
	v_mul_f32_e32 v0, v16, v64
	v_mul_f32_e32 v0, v90, v0
	v_cvt_pk_bf16_f32 v0, v0, v144
	ds_write_b16 v68, v0 offset:64
	v_mul_f32_e32 v0, v32, v64
	v_mul_f32_e32 v0, v91, v0
	v_cvt_pk_bf16_f32 v0, v0, v144
	ds_write_b16 v68, v0 offset:128
	v_mul_f32_e32 v0, v48, v64
	v_mul_f32_e32 v0, v85, v0
	v_cvt_pk_bf16_f32 v0, v0, v144
	ds_write_b16 v68, v0 offset:192
	v_rcp_f32_e32 v0, v81
	s_nop 0
	v_mul_f32_e32 v0, v84, v0
	v_fma_f32 v16, -v17, v0, v73
	v_fma_f32 v1, -v1, v0, v77
	v_mul_f32_e32 v17, v16, v16
	v_fmac_f32_e32 v17, v1, v1
	v_fma_f32 v32, -v33, v0, v69
	v_fmac_f32_e32 v17, v32, v32
	v_fma_f32 v0, -v49, v0, v65
	v_fmac_f32_e32 v17, v0, v0
	ds_bpermute_b32 v33, v145, v17
	s_waitcnt lgkmcnt(0)
	v_add_f32_e32 v17, v17, v33
	ds_bpermute_b32 v33, v210, v17
	s_waitcnt lgkmcnt(0)
	v_add_f32_e32 v17, v17, v33
	ds_bpermute_b32 v33, v211, v17
	s_waitcnt lgkmcnt(0)
	v_add_f32_e32 v17, v17, v33
	ds_bpermute_b32 v33, v212, v17
	s_waitcnt lgkmcnt(0)
	v_add_f32_e32 v17, v17, v33
	ds_bpermute_b32 v33, v213, v17
	s_waitcnt lgkmcnt(0)
	v_add_f32_e32 v17, v17, v33
	v_fmamk_f32 v17, v17, 0x3c000000, v233
	v_rsq_f32_e32 v17, v17
	s_nop 0
	v_mul_f32_e32 v1, v1, v17
	v_mul_f32_e32 v1, v89, v1
	v_cvt_pk_bf16_f32 v1, v1, v144
	ds_write_b16 v68, v1 offset:272
	v_mul_f32_e32 v1, v16, v17
	v_mul_f32_e32 v1, v90, v1
	v_cvt_pk_bf16_f32 v1, v1, v144
	ds_write_b16 v68, v1 offset:336
	v_mul_f32_e32 v1, v32, v17
	v_mul_f32_e32 v0, v0, v17
	v_mul_f32_e32 v1, v91, v1
	v_mul_f32_e32 v0, v85, v0
	v_cvt_pk_bf16_f32 v1, v1, v144
	ds_write_b16 v68, v1 offset:400
	v_cvt_pk_bf16_f32 v0, v0, v144
	ds_write_b16 v68, v0 offset:464
	v_rcp_f32_e32 v0, v82
	s_nop 0
	v_mul_f32_e32 v0, v84, v0
	v_fma_f32 v1, -v2, v0, v78
	v_fma_f32 v2, -v18, v0, v74
	v_mul_f32_e32 v16, v2, v2
	v_fmac_f32_e32 v16, v1, v1
	v_fma_f32 v17, -v34, v0, v70
	v_fmac_f32_e32 v16, v17, v17
	v_fma_f32 v0, -v50, v0, v66
	v_fmac_f32_e32 v16, v0, v0
	ds_bpermute_b32 v18, v145, v16
	s_waitcnt lgkmcnt(0)
	v_add_f32_e32 v16, v16, v18
	ds_bpermute_b32 v18, v210, v16
	s_waitcnt lgkmcnt(0)
	v_add_f32_e32 v16, v16, v18
	ds_bpermute_b32 v18, v211, v16
	s_waitcnt lgkmcnt(0)
	v_add_f32_e32 v16, v16, v18
	ds_bpermute_b32 v18, v212, v16
	s_waitcnt lgkmcnt(0)
	v_add_f32_e32 v16, v16, v18
	ds_bpermute_b32 v18, v213, v16
	s_waitcnt lgkmcnt(0)
	v_add_f32_e32 v16, v16, v18
	v_fmamk_f32 v16, v16, 0x3c000000, v233
	v_rsq_f32_e32 v16, v16
	s_nop 0
	v_mul_f32_e32 v1, v1, v16
	v_mul_f32_e32 v1, v89, v1
	v_cvt_pk_bf16_f32 v1, v1, v144
	ds_write_b16 v68, v1 offset:544
	v_mul_f32_e32 v1, v2, v16
	v_mul_f32_e32 v1, v90, v1
	v_cvt_pk_bf16_f32 v1, v1, v144
	ds_write_b16 v68, v1 offset:608
	v_mul_f32_e32 v1, v17, v16
	v_mul_f32_e32 v0, v0, v16
	v_mul_f32_e32 v1, v91, v1
	v_mul_f32_e32 v0, v85, v0
	v_cvt_pk_bf16_f32 v1, v1, v144
	ds_write_b16 v68, v1 offset:672
	v_cvt_pk_bf16_f32 v0, v0, v144
	ds_write_b16 v68, v0 offset:736
	v_rcp_f32_e32 v0, v83
	s_nop 0
	v_mul_f32_e32 v0, v84, v0
	v_fma_f32 v2, -v19, v0, v75
	v_fma_f32 v1, -v3, v0, v79
	v_mul_f32_e32 v3, v2, v2
	v_fmac_f32_e32 v3, v1, v1
	v_fma_f32 v16, -v35, v0, v71
	v_fmac_f32_e32 v3, v16, v16
	v_fma_f32 v0, -v51, v0, v67
	v_fmac_f32_e32 v3, v0, v0
	ds_bpermute_b32 v17, v145, v3
	s_waitcnt lgkmcnt(0)
; __device__ __forceinline__ unsigned cvtpk(float lo, float hi) { unsigned r; asm volatile("v_cvt_pk_bf16_f32 %0, %1, %2" : "=v"(r) : "v"(lo), "v"(hi)); return r; }
; template <bool GRPB> __device__ __forceinline__ void attn_pass(const float mbK, const float bmax2, const int pass, float* __restrict__ scr, bf16* __restrict__ mixrow, const float lam, const float* __restrict__ gsub, const float one_m_li, ...
;     ...
;       for (int i = 0; i < 4; ++i) { const float rl = __builtin_amdgcn_rcpf(lv[i]) * lam_; float dv[4]; float sq = 0.f;
; #pragma unroll
;         for (int d0 = 0; d0 < 4; ++d0) { dv[d0] = av[d0][i] - rl * o[d0][4 * r4 + i]; sq += dv[d0] * dv[d0]; }
;         sq += __shfl_xor(sq, 1); sq += __shfl_xor(sq, 2); sq += __shfl_xor(sq, 4); sq += __shfl_xor(sq, 8); sq += __shfl_xor(sq, 16);
;         const float rs = __builtin_amdgcn_rsqf(sq * (1.0f / 128.0f) + EPS);
;         unsigned short* orow = (unsigned short*)(ost_e + (8 * r4 + 4 * hi + i) * OST_PITCH) + r32;
; #pragma unroll
;         for (int d0 = 0; d0 < 4; ++d0) orow[d0 * 32] = (unsigned short)(cvtpk(dv[d0] * rs * g[d0], 0.f) & 0xffffu); } }
	v_add_f32_e32 v3, v3, v17
	ds_bpermute_b32 v17, v210, v3
	s_waitcnt lgkmcnt(0)
	v_add_f32_e32 v3, v3, v17
	ds_bpermute_b32 v17, v211, v3
	s_waitcnt lgkmcnt(0)
	v_add_f32_e32 v3, v3, v17
	ds_bpermute_b32 v17, v212, v3
	s_waitcnt lgkmcnt(0)
	v_add_f32_e32 v3, v3, v17
	ds_bpermute_b32 v17, v213, v3
	s_waitcnt lgkmcnt(0)
	v_add_f32_e32 v3, v3, v17
	v_fmamk_f32 v3, v3, 0x3c000000, v233
	v_rsq_f32_e32 v3, v3
	s_nop 0
	v_mul_f32_e32 v1, v1, v3
	v_mul_f32_e32 v1, v89, v1
	v_cvt_pk_bf16_f32 v1, v1, v144
	ds_write_b16 v68, v1 offset:816
	v_mul_f32_e32 v1, v2, v3
	v_mul_f32_e32 v1, v90, v1
	v_cvt_pk_bf16_f32 v1, v1, v144
	ds_write_b16 v68, v1 offset:880
	v_mul_f32_e32 v1, v16, v3
	v_mul_f32_e32 v0, v0, v3
	v_mul_f32_e32 v1, v91, v1
	v_mul_f32_e32 v0, v85, v0
	v_cvt_pk_bf16_f32 v1, v1, v144
	ds_write_b16 v68, v1 offset:944
	v_cvt_pk_bf16_f32 v0, v0, v144
	ds_write_b16 v68, v0 offset:1008
	ds_read_b128 v[64:67], v92 offset:32
	s_waitcnt lgkmcnt(0)
	v_rcp_f32_e32 v64, v64
	s_nop 0
	v_mul_f32_e32 v64, v84, v64
	s_waitcnt vmcnt(11)
	v_fma_f32 v4, -v4, v64, v96
	s_waitcnt vmcnt(10)
	v_fma_f32 v20, -v20, v64, v100
	v_mul_f32_e32 v32, v20, v20
	v_fmac_f32_e32 v32, v4, v4
	s_waitcnt vmcnt(9)
	v_fma_f32 v16, -v36, v64, v104
	v_fmac_f32_e32 v32, v16, v16
	s_waitcnt vmcnt(8)
	v_fma_f32 v0, -v52, v64, v108
	v_fmac_f32_e32 v32, v0, v0
	ds_bpermute_b32 v36, v145, v32
	s_waitcnt lgkmcnt(0)
	v_add_f32_e32 v32, v32, v36
	ds_bpermute_b32 v36, v210, v32
	s_waitcnt lgkmcnt(0)
	v_add_f32_e32 v32, v32, v36
	ds_bpermute_b32 v36, v211, v32
	s_waitcnt lgkmcnt(0)
	v_add_f32_e32 v32, v32, v36
	ds_bpermute_b32 v36, v212, v32
	s_waitcnt lgkmcnt(0)
	v_add_f32_e32 v32, v32, v36
	ds_bpermute_b32 v36, v213, v32
	s_waitcnt lgkmcnt(0)
	v_add_f32_e32 v32, v32, v36
	v_fmamk_f32 v32, v32, 0x3c000000, v233
	v_rsq_f32_e32 v32, v32
	s_nop 0
	v_mul_f32_e32 v4, v4, v32
	v_mul_f32_e32 v4, v89, v4
	v_cvt_pk_bf16_f32 v4, v4, v144
	ds_write_b16 v68, v4 offset:2176
	v_mul_f32_e32 v4, v20, v32
	v_mul_f32_e32 v4, v90, v4
	v_cvt_pk_bf16_f32 v4, v4, v144
	ds_write_b16 v68, v4 offset:2240
	v_mul_f32_e32 v4, v16, v32
	v_mul_f32_e32 v0, v0, v32
	v_mul_f32_e32 v4, v91, v4
	v_mul_f32_e32 v0, v85, v0
	v_cvt_pk_bf16_f32 v4, v4, v144
	ds_write_b16 v68, v4 offset:2304
	v_cvt_pk_bf16_f32 v0, v0, v144
	ds_write_b16 v68, v0 offset:2368
	v_rcp_f32_e32 v0, v65
	s_nop 0
	v_mul_f32_e32 v0, v84, v0
	v_fma_f32 v4, -v5, v0, v97
	v_fma_f32 v5, -v21, v0, v101
	v_mul_f32_e32 v16, v5, v5
	v_fmac_f32_e32 v16, v4, v4
	v_fma_f32 v17, -v37, v0, v105
	v_fmac_f32_e32 v16, v17, v17
	v_fma_f32 v0, -v53, v0, v109
	v_fmac_f32_e32 v16, v0, v0
	ds_bpermute_b32 v1, v145, v16
	s_waitcnt lgkmcnt(0)
	v_add_f32_e32 v1, v16, v1
	ds_bpermute_b32 v16, v210, v1
	s_waitcnt lgkmcnt(0)
	v_add_f32_e32 v1, v1, v16
	ds_bpermute_b32 v16, v211, v1
	s_waitcnt lgkmcnt(0)
	v_add_f32_e32 v1, v1, v16
	ds_bpermute_b32 v16, v212, v1
	s_waitcnt lgkmcnt(0)
	v_add_f32_e32 v1, v1, v16
	ds_bpermute_b32 v16, v213, v1
	s_waitcnt lgkmcnt(0)
	v_add_f32_e32 v1, v1, v16
	v_fmamk_f32 v1, v1, 0x3c000000, v233
	v_rsq_f32_e32 v1, v1
	s_nop 0
	v_mul_f32_e32 v4, v4, v1
	v_mul_f32_e32 v4, v89, v4
	v_cvt_pk_bf16_f32 v4, v4, v144
	ds_write_b16 v68, v4 offset:2448
	v_mul_f32_e32 v4, v5, v1
	v_mul_f32_e32 v4, v90, v4
	v_cvt_pk_bf16_f32 v4, v4, v144
	ds_write_b16 v68, v4 offset:2512
	v_mul_f32_e32 v4, v17, v1
	v_mul_f32_e32 v0, v0, v1
	v_mul_f32_e32 v4, v91, v4
	v_mul_f32_e32 v0, v85, v0
	v_cvt_pk_bf16_f32 v4, v4, v144
	ds_write_b16 v68, v4 offset:2576
	v_cvt_pk_bf16_f32 v0, v0, v144
	ds_write_b16 v68, v0 offset:2640
	v_rcp_f32_e32 v0, v66
	s_nop 0
	v_mul_f32_e32 v0, v84, v0
	v_fma_f32 v4, -v22, v0, v102
	v_fma_f32 v1, -v6, v0, v98
	v_mul_f32_e32 v5, v4, v4
	v_fmac_f32_e32 v5, v1, v1
	v_fma_f32 v6, -v38, v0, v106
	v_fmac_f32_e32 v5, v6, v6
	v_fma_f32 v0, -v54, v0, v110
	v_fmac_f32_e32 v5, v0, v0
	ds_bpermute_b32 v2, v145, v5
	s_waitcnt lgkmcnt(0)
	v_add_f32_e32 v2, v5, v2
	ds_bpermute_b32 v5, v210, v2
	s_waitcnt lgkmcnt(0)
	v_add_f32_e32 v2, v2, v5
	ds_bpermute_b32 v5, v211, v2
	s_waitcnt lgkmcnt(0)
	v_add_f32_e32 v2, v2, v5
	ds_bpermute_b32 v5, v212, v2
	s_waitcnt lgkmcnt(0)
	v_add_f32_e32 v2, v2, v5
	ds_bpermute_b32 v5, v213, v2
	s_waitcnt lgkmcnt(0)
	v_add_f32_e32 v2, v2, v5
	v_fmamk_f32 v2, v2, 0x3c000000, v233
	v_rsq_f32_e32 v2, v2
	s_nop 0
	v_mul_f32_e32 v1, v1, v2
	v_mul_f32_e32 v1, v89, v1
	v_cvt_pk_bf16_f32 v1, v1, v144
	ds_write_b16 v68, v1 offset:2720
	v_mul_f32_e32 v1, v4, v2
	v_mul_f32_e32 v1, v90, v1
	v_cvt_pk_bf16_f32 v1, v1, v144
	ds_write_b16 v68, v1 offset:2784
	v_mul_f32_e32 v1, v6, v2
	v_mul_f32_e32 v0, v0, v2
	v_mul_f32_e32 v1, v91, v1
	v_mul_f32_e32 v0, v85, v0
	v_cvt_pk_bf16_f32 v1, v1, v144
	ds_write_b16 v68, v1 offset:2848
	v_cvt_pk_bf16_f32 v0, v0, v144
	ds_write_b16 v68, v0 offset:2912
	v_rcp_f32_e32 v0, v67
	s_nop 0
	v_mul_f32_e32 v0, v84, v0
	v_fma_f32 v2, -v23, v0, v103
	v_fma_f32 v1, -v7, v0, v99
	v_mul_f32_e32 v4, v2, v2
	v_fmac_f32_e32 v4, v1, v1
	v_fma_f32 v5, -v39, v0, v107
	v_fmac_f32_e32 v4, v5, v5
	v_fma_f32 v0, -v55, v0, v111
	v_fmac_f32_e32 v4, v0, v0
	ds_bpermute_b32 v3, v145, v4
	s_waitcnt lgkmcnt(0)
	v_add_f32_e32 v3, v4, v3
	ds_bpermute_b32 v4, v210, v3
	s_waitcnt lgkmcnt(0)
	v_add_f32_e32 v3, v3, v4
	ds_bpermute_b32 v4, v211, v3
	s_waitcnt lgkmcnt(0)
	v_add_f32_e32 v3, v3, v4
	ds_bpermute_b32 v4, v212, v3
	s_waitcnt lgkmcnt(0)
	v_add_f32_e32 v3, v3, v4
	ds_bpermute_b32 v4, v213, v3
	s_waitcnt lgkmcnt(0)
; __device__ __forceinline__ unsigned cvtpk(float lo, float hi) { unsigned r; asm volatile("v_cvt_pk_bf16_f32 %0, %1, %2" : "=v"(r) : "v"(lo), "v"(hi)); return r; }
; template <bool GRPB> __device__ __forceinline__ void attn_pass(const float mbK, const float bmax2, const int pass, float* __restrict__ scr, bf16* __restrict__ mixrow, const float lam, const float* __restrict__ gsub, const float one_m_li, ...
;     ...
;       for (int i = 0; i < 4; ++i) { const float rl = __builtin_amdgcn_rcpf(lv[i]) * lam_; float dv[4]; float sq = 0.f;
; #pragma unroll
;         for (int d0 = 0; d0 < 4; ++d0) { dv[d0] = av[d0][i] - rl * o[d0][4 * r4 + i]; sq += dv[d0] * dv[d0]; }
;         sq += __shfl_xor(sq, 1); sq += __shfl_xor(sq, 2); sq += __shfl_xor(sq, 4); sq += __shfl_xor(sq, 8); sq += __shfl_xor(sq, 16);
;         const float rs = __builtin_amdgcn_rsqf(sq * (1.0f / 128.0f) + EPS);
;         unsigned short* orow = (unsigned short*)(ost_e + (8 * r4 + 4 * hi + i) * OST_PITCH) + r32;
; #pragma unroll
;         for (int d0 = 0; d0 < 4; ++d0) orow[d0 * 32] = (unsigned short)(cvtpk(dv[d0] * rs * g[d0], 0.f) & 0xffffu); } }
	v_add_f32_e32 v3, v3, v4
	v_fmamk_f32 v3, v3, 0x3c000000, v233
	v_rsq_f32_e32 v3, v3
	s_nop 0
	v_mul_f32_e32 v1, v1, v3
	v_mul_f32_e32 v1, v89, v1
	v_cvt_pk_bf16_f32 v1, v1, v144
	ds_write_b16 v68, v1 offset:2992
	v_mul_f32_e32 v1, v2, v3
	v_mul_f32_e32 v1, v90, v1
	v_cvt_pk_bf16_f32 v1, v1, v144
	ds_write_b16 v68, v1 offset:3056
	v_mul_f32_e32 v1, v5, v3
	v_mul_f32_e32 v0, v0, v3
	v_mul_f32_e32 v1, v91, v1
	v_mul_f32_e32 v0, v85, v0
	v_cvt_pk_bf16_f32 v1, v1, v144
	ds_write_b16 v68, v1 offset:3120
	v_cvt_pk_bf16_f32 v0, v0, v144
	ds_write_b16 v68, v0 offset:3184
	ds_read_b128 v[32:35], v92 offset:64
	s_waitcnt lgkmcnt(0)
	v_rcp_f32_e32 v32, v32
	s_nop 0
	v_mul_f32_e32 v32, v84, v32
	s_waitcnt vmcnt(7)
	v_fma_f32 v8, -v8, v32, v112
	s_waitcnt vmcnt(6)
	v_fma_f32 v16, -v24, v32, v116
	v_mul_f32_e32 v20, v16, v16
	v_fmac_f32_e32 v20, v8, v8
	s_waitcnt vmcnt(5)
	v_fma_f32 v4, -v40, v32, v120
	v_fmac_f32_e32 v20, v4, v4
	s_waitcnt vmcnt(4)
	v_fma_f32 v0, -v56, v32, v124
	v_fmac_f32_e32 v20, v0, v0
	ds_bpermute_b32 v24, v145, v20
	s_waitcnt lgkmcnt(0)
	v_add_f32_e32 v20, v20, v24
	ds_bpermute_b32 v24, v210, v20
	s_waitcnt lgkmcnt(0)
	v_add_f32_e32 v20, v20, v24
	ds_bpermute_b32 v24, v211, v20
	s_waitcnt lgkmcnt(0)
	v_add_f32_e32 v20, v20, v24
	ds_bpermute_b32 v24, v212, v20
	s_waitcnt lgkmcnt(0)
	v_add_f32_e32 v20, v20, v24
	ds_bpermute_b32 v24, v213, v20
	s_waitcnt lgkmcnt(0)
	v_add_f32_e32 v20, v20, v24
	v_fmamk_f32 v20, v20, 0x3c000000, v233
	v_rsq_f32_e32 v20, v20
	s_nop 0
	v_mul_f32_e32 v8, v8, v20
	v_mul_f32_e32 v8, v89, v8
	v_cvt_pk_bf16_f32 v8, v8, v144
	ds_write_b16 v68, v8 offset:4352
	v_mul_f32_e32 v8, v16, v20
	v_mul_f32_e32 v4, v4, v20
	v_mul_f32_e32 v0, v0, v20
	v_mul_f32_e32 v8, v90, v8
	v_mul_f32_e32 v4, v91, v4
	v_mul_f32_e32 v0, v85, v0
	v_cvt_pk_bf16_f32 v8, v8, v144
	ds_write_b16 v68, v8 offset:4416
	v_cvt_pk_bf16_f32 v4, v4, v144
	ds_write_b16 v68, v4 offset:4480
	v_cvt_pk_bf16_f32 v0, v0, v144
	ds_write_b16 v68, v0 offset:4544
	v_rcp_f32_e32 v0, v33
	s_nop 0
	v_mul_f32_e32 v0, v84, v0
	v_fma_f32 v8, -v25, v0, v117
	v_fma_f32 v4, -v9, v0, v113
	v_mul_f32_e32 v9, v8, v8
	v_fmac_f32_e32 v9, v4, v4
	v_fma_f32 v5, -v41, v0, v121
	v_fmac_f32_e32 v9, v5, v5
	v_fma_f32 v0, -v57, v0, v125
	v_fmac_f32_e32 v9, v0, v0
	ds_bpermute_b32 v1, v145, v9
	s_waitcnt lgkmcnt(0)
	v_add_f32_e32 v1, v9, v1
	ds_bpermute_b32 v9, v210, v1
	s_waitcnt lgkmcnt(0)
	v_add_f32_e32 v1, v1, v9
	ds_bpermute_b32 v9, v211, v1
	s_waitcnt lgkmcnt(0)
	v_add_f32_e32 v1, v1, v9
	ds_bpermute_b32 v9, v212, v1
	s_waitcnt lgkmcnt(0)
	v_add_f32_e32 v1, v1, v9
	ds_bpermute_b32 v9, v213, v1
	s_waitcnt lgkmcnt(0)
	v_add_f32_e32 v1, v1, v9
	v_fmamk_f32 v1, v1, 0x3c000000, v233
	v_rsq_f32_e32 v1, v1
	s_nop 0
	v_mul_f32_e32 v4, v4, v1
	v_mul_f32_e32 v4, v89, v4
	v_cvt_pk_bf16_f32 v4, v4, v144
	ds_write_b16 v68, v4 offset:4624
	v_mul_f32_e32 v4, v8, v1
	v_mul_f32_e32 v4, v90, v4
	v_cvt_pk_bf16_f32 v4, v4, v144
	ds_write_b16 v68, v4 offset:4688
	v_mul_f32_e32 v4, v5, v1
	v_mul_f32_e32 v0, v0, v1
	v_mul_f32_e32 v4, v91, v4
	v_mul_f32_e32 v0, v85, v0
	v_cvt_pk_bf16_f32 v4, v4, v144
	ds_write_b16 v68, v4 offset:4752
	v_cvt_pk_bf16_f32 v0, v0, v144
	ds_write_b16 v68, v0 offset:4816
	v_rcp_f32_e32 v0, v34
	s_nop 0
	v_mul_f32_e32 v0, v84, v0
	v_fma_f32 v4, -v26, v0, v118
	v_fma_f32 v1, -v10, v0, v114
	v_mul_f32_e32 v5, v4, v4
	v_fmac_f32_e32 v5, v1, v1
	v_fma_f32 v6, -v42, v0, v122
	v_fmac_f32_e32 v5, v6, v6
	v_fma_f32 v0, -v58, v0, v126
	v_fmac_f32_e32 v5, v0, v0
	ds_bpermute_b32 v2, v145, v5
	s_waitcnt lgkmcnt(0)
	v_add_f32_e32 v2, v5, v2
	ds_bpermute_b32 v5, v210, v2
	s_waitcnt lgkmcnt(0)
	v_add_f32_e32 v2, v2, v5
	ds_bpermute_b32 v5, v211, v2
	s_waitcnt lgkmcnt(0)
	v_add_f32_e32 v2, v2, v5
	ds_bpermute_b32 v5, v212, v2
	s_waitcnt lgkmcnt(0)
	v_add_f32_e32 v2, v2, v5
	ds_bpermute_b32 v5, v213, v2
	s_waitcnt lgkmcnt(0)
	v_add_f32_e32 v2, v2, v5
	v_fmamk_f32 v2, v2, 0x3c000000, v233
	v_rsq_f32_e32 v2, v2
	s_nop 0
	v_mul_f32_e32 v1, v1, v2
	v_mul_f32_e32 v1, v89, v1
	v_cvt_pk_bf16_f32 v1, v1, v144
	ds_write_b16 v68, v1 offset:4896
	v_mul_f32_e32 v1, v4, v2
	v_mul_f32_e32 v1, v90, v1
	v_cvt_pk_bf16_f32 v1, v1, v144
	ds_write_b16 v68, v1 offset:4960
	v_mul_f32_e32 v1, v6, v2
	v_mul_f32_e32 v0, v0, v2
	v_mul_f32_e32 v1, v91, v1
	v_mul_f32_e32 v0, v85, v0
	v_cvt_pk_bf16_f32 v1, v1, v144
	ds_write_b16 v68, v1 offset:5024
	v_cvt_pk_bf16_f32 v0, v0, v144
	ds_write_b16 v68, v0 offset:5088
	v_rcp_f32_e32 v0, v35
	s_nop 0
	v_mul_f32_e32 v0, v84, v0
	v_fma_f32 v2, -v27, v0, v119
	v_fma_f32 v1, -v11, v0, v115
	v_mul_f32_e32 v4, v2, v2
	v_fmac_f32_e32 v4, v1, v1
	v_fma_f32 v5, -v43, v0, v123
	v_fmac_f32_e32 v4, v5, v5
	v_fma_f32 v0, -v59, v0, v127
	v_fmac_f32_e32 v4, v0, v0
	ds_bpermute_b32 v3, v145, v4
	s_waitcnt lgkmcnt(0)
	v_add_f32_e32 v3, v4, v3
	ds_bpermute_b32 v4, v210, v3
	s_waitcnt lgkmcnt(0)
	v_add_f32_e32 v3, v3, v4
	ds_bpermute_b32 v4, v211, v3
	s_waitcnt lgkmcnt(0)
	v_add_f32_e32 v3, v3, v4
	ds_bpermute_b32 v4, v212, v3
	s_waitcnt lgkmcnt(0)
	v_add_f32_e32 v3, v3, v4
	ds_bpermute_b32 v4, v213, v3
	s_waitcnt lgkmcnt(0)
; __device__ __forceinline__ unsigned cvtpk(float lo, float hi) { unsigned r; asm volatile("v_cvt_pk_bf16_f32 %0, %1, %2" : "=v"(r) : "v"(lo), "v"(hi)); return r; }
; template <bool GRPB> __device__ __forceinline__ void attn_pass(const float mbK, const float bmax2, const int pass, float* __restrict__ scr, bf16* __restrict__ mixrow, const float lam, const float* __restrict__ gsub, const float one_m_li, ...
;     ...
;       for (int i = 0; i < 4; ++i) { const float rl = __builtin_amdgcn_rcpf(lv[i]) * lam_; float dv[4]; float sq = 0.f;
; #pragma unroll
;         for (int d0 = 0; d0 < 4; ++d0) { dv[d0] = av[d0][i] - rl * o[d0][4 * r4 + i]; sq += dv[d0] * dv[d0]; }
;         sq += __shfl_xor(sq, 1); sq += __shfl_xor(sq, 2); sq += __shfl_xor(sq, 4); sq += __shfl_xor(sq, 8); sq += __shfl_xor(sq, 16);
;         const float rs = __builtin_amdgcn_rsqf(sq * (1.0f / 128.0f) + EPS);
;         unsigned short* orow = (unsigned short*)(ost_e + (8 * r4 + 4 * hi + i) * OST_PITCH) + r32;
; #pragma unroll
;         for (int d0 = 0; d0 < 4; ++d0) orow[d0 * 32] = (unsigned short)(cvtpk(dv[d0] * rs * g[d0], 0.f) & 0xffffu); } }
	v_add_f32_e32 v3, v3, v4
	v_fmamk_f32 v3, v3, 0x3c000000, v233
	v_rsq_f32_e32 v3, v3
	s_nop 0
	v_mul_f32_e32 v1, v1, v3
	v_mul_f32_e32 v1, v89, v1
	v_cvt_pk_bf16_f32 v1, v1, v144
	ds_write_b16 v68, v1 offset:5168
	v_mul_f32_e32 v1, v2, v3
	v_mul_f32_e32 v1, v90, v1
	v_cvt_pk_bf16_f32 v1, v1, v144
	ds_write_b16 v68, v1 offset:5232
	v_mul_f32_e32 v1, v5, v3
	v_mul_f32_e32 v0, v0, v3
	v_mul_f32_e32 v1, v91, v1
	v_mul_f32_e32 v0, v85, v0
	v_cvt_pk_bf16_f32 v1, v1, v144
	ds_write_b16 v68, v1 offset:5296
	v_cvt_pk_bf16_f32 v0, v0, v144
	ds_write_b16 v68, v0 offset:5360
	ds_read_b128 v[20:23], v92 offset:96
	s_waitcnt lgkmcnt(0)
	v_rcp_f32_e32 v20, v20
	s_nop 0
	v_mul_f32_e32 v20, v84, v20
	s_waitcnt vmcnt(3)
	v_fma_f32 v8, -v12, v20, v128
	s_waitcnt vmcnt(2)
	v_fma_f32 v12, -v28, v20, v132
	v_mul_f32_e32 v16, v12, v12
	v_fmac_f32_e32 v16, v8, v8
	s_waitcnt vmcnt(1)
	v_fma_f32 v4, -v44, v20, v136
	v_fmac_f32_e32 v16, v4, v4
	s_waitcnt vmcnt(0)
	v_fma_f32 v0, -v60, v20, v140
	v_fmac_f32_e32 v16, v0, v0
	ds_bpermute_b32 v20, v145, v16
	s_waitcnt lgkmcnt(0)
	v_add_f32_e32 v16, v16, v20
	ds_bpermute_b32 v20, v210, v16
	s_waitcnt lgkmcnt(0)
	v_add_f32_e32 v16, v16, v20
	ds_bpermute_b32 v20, v211, v16
	s_waitcnt lgkmcnt(0)
	v_add_f32_e32 v16, v16, v20
	ds_bpermute_b32 v20, v212, v16
	s_waitcnt lgkmcnt(0)
	v_add_f32_e32 v16, v16, v20
	ds_bpermute_b32 v20, v213, v16
	s_waitcnt lgkmcnt(0)
	v_add_f32_e32 v16, v16, v20
	v_fmamk_f32 v16, v16, 0x3c000000, v233
	v_rsq_f32_e32 v16, v16
	s_nop 0
	v_mul_f32_e32 v8, v8, v16
	v_mul_f32_e32 v8, v89, v8
	v_cvt_pk_bf16_f32 v8, v8, v144
	ds_write_b16 v68, v8 offset:6528
	v_mul_f32_e32 v8, v12, v16
	v_mul_f32_e32 v4, v4, v16
	v_mul_f32_e32 v0, v0, v16
	v_mul_f32_e32 v8, v90, v8
	v_mul_f32_e32 v4, v91, v4
	v_mul_f32_e32 v0, v85, v0
	v_cvt_pk_bf16_f32 v8, v8, v144
	ds_write_b16 v68, v8 offset:6592
	v_cvt_pk_bf16_f32 v4, v4, v144
	ds_write_b16 v68, v4 offset:6656
	v_cvt_pk_bf16_f32 v0, v0, v144
	ds_write_b16 v68, v0 offset:6720
	v_rcp_f32_e32 v0, v21
	s_nop 0
	v_mul_f32_e32 v0, v84, v0
	v_fma_f32 v8, -v29, v0, v133
	v_fma_f32 v4, -v13, v0, v129
	v_mul_f32_e32 v9, v8, v8
	v_fmac_f32_e32 v9, v4, v4
	v_fma_f32 v5, -v45, v0, v137
	v_fmac_f32_e32 v9, v5, v5
	v_fma_f32 v0, -v61, v0, v141
	v_fmac_f32_e32 v9, v0, v0
	ds_bpermute_b32 v1, v145, v9
	s_waitcnt lgkmcnt(0)
	v_add_f32_e32 v1, v9, v1
	ds_bpermute_b32 v9, v210, v1
	s_waitcnt lgkmcnt(0)
	v_add_f32_e32 v1, v1, v9
	ds_bpermute_b32 v9, v211, v1
	s_waitcnt lgkmcnt(0)
	v_add_f32_e32 v1, v1, v9
	ds_bpermute_b32 v9, v212, v1
	s_waitcnt lgkmcnt(0)
	v_add_f32_e32 v1, v1, v9
	ds_bpermute_b32 v9, v213, v1
	s_waitcnt lgkmcnt(0)
	v_add_f32_e32 v1, v1, v9
	v_fmamk_f32 v1, v1, 0x3c000000, v233
	v_rsq_f32_e32 v1, v1
	s_nop 0
	v_mul_f32_e32 v4, v4, v1
	v_mul_f32_e32 v4, v89, v4
	v_cvt_pk_bf16_f32 v4, v4, v144
	ds_write_b16 v68, v4 offset:6800
	v_mul_f32_e32 v4, v8, v1
	v_mul_f32_e32 v4, v90, v4
	v_cvt_pk_bf16_f32 v4, v4, v144
	ds_write_b16 v68, v4 offset:6864
	v_mul_f32_e32 v4, v5, v1
	v_mul_f32_e32 v0, v0, v1
	v_mul_f32_e32 v4, v91, v4
	v_mul_f32_e32 v0, v85, v0
	v_cvt_pk_bf16_f32 v4, v4, v144
	ds_write_b16 v68, v4 offset:6928
	v_cvt_pk_bf16_f32 v0, v0, v144
	ds_write_b16 v68, v0 offset:6992
	v_rcp_f32_e32 v0, v22
	s_nop 0
	v_mul_f32_e32 v0, v84, v0
	v_fma_f32 v4, -v30, v0, v134
	v_fma_f32 v1, -v14, v0, v130
	v_mul_f32_e32 v5, v4, v4
	v_fmac_f32_e32 v5, v1, v1
	v_fma_f32 v6, -v46, v0, v138
	v_fmac_f32_e32 v5, v6, v6
	v_fma_f32 v0, -v62, v0, v142
	v_fmac_f32_e32 v5, v0, v0
	ds_bpermute_b32 v2, v145, v5
	s_waitcnt lgkmcnt(0)
	v_add_f32_e32 v2, v5, v2
	ds_bpermute_b32 v5, v210, v2
	s_waitcnt lgkmcnt(0)
	v_add_f32_e32 v2, v2, v5
	ds_bpermute_b32 v5, v211, v2
	s_waitcnt lgkmcnt(0)
	v_add_f32_e32 v2, v2, v5
	ds_bpermute_b32 v5, v212, v2
	s_waitcnt lgkmcnt(0)
	v_add_f32_e32 v2, v2, v5
	ds_bpermute_b32 v5, v213, v2
	s_waitcnt lgkmcnt(0)
	v_add_f32_e32 v2, v2, v5
	v_fmamk_f32 v2, v2, 0x3c000000, v233
	v_rsq_f32_e32 v2, v2
	s_nop 0
	v_mul_f32_e32 v1, v1, v2
	v_mul_f32_e32 v1, v89, v1
	v_cvt_pk_bf16_f32 v1, v1, v144
	ds_write_b16 v68, v1 offset:7072
	v_mul_f32_e32 v1, v4, v2
	v_mul_f32_e32 v1, v90, v1
	v_cvt_pk_bf16_f32 v1, v1, v144
	ds_write_b16 v68, v1 offset:7136
	v_mul_f32_e32 v1, v6, v2
	v_mul_f32_e32 v0, v0, v2
	v_mul_f32_e32 v1, v91, v1
	v_mul_f32_e32 v0, v85, v0
	v_cvt_pk_bf16_f32 v1, v1, v144
	ds_write_b16 v68, v1 offset:7200
	v_cvt_pk_bf16_f32 v0, v0, v144
	ds_write_b16 v68, v0 offset:7264
	v_rcp_f32_e32 v0, v23
	s_nop 0
	v_mul_f32_e32 v0, v84, v0
	v_fma_f32 v2, -v31, v0, v135
	v_fma_f32 v1, -v15, v0, v131
	v_mul_f32_e32 v4, v2, v2
	v_fmac_f32_e32 v4, v1, v1
	v_fma_f32 v5, -v47, v0, v139
	v_fmac_f32_e32 v4, v5, v5
	v_fma_f32 v0, -v63, v0, v143
	v_fmac_f32_e32 v4, v0, v0
	ds_bpermute_b32 v3, v145, v4
	s_waitcnt lgkmcnt(0)
	v_add_f32_e32 v3, v4, v3
	ds_bpermute_b32 v4, v210, v3
	s_waitcnt lgkmcnt(0)
	v_add_f32_e32 v3, v3, v4
	ds_bpermute_b32 v4, v211, v3
	s_waitcnt lgkmcnt(0)
	v_add_f32_e32 v3, v3, v4
	ds_bpermute_b32 v4, v212, v3
	s_waitcnt lgkmcnt(0)
	v_add_f32_e32 v3, v3, v4
	ds_bpermute_b32 v4, v213, v3
	s_waitcnt lgkmcnt(0)
	v_add_f32_e32 v3, v3, v4
	v_fmamk_f32 v3, v3, 0x3c000000, v233
	v_rsq_f32_e32 v3, v3
	s_nop 0
	v_mul_f32_e32 v1, v1, v3
	v_mul_f32_e32 v1, v89, v1
	v_cvt_pk_bf16_f32 v1, v1, v144
	ds_write_b16 v68, v1 offset:7344
	v_mul_f32_e32 v1, v2, v3
	v_mul_f32_e32 v1, v90, v1
	v_cvt_pk_bf16_f32 v1, v1, v144
	ds_write_b16 v68, v1 offset:7408
	v_mul_f32_e32 v1, v5, v3
	v_mul_f32_e32 v0, v0, v3
	v_mul_f32_e32 v1, v91, v1
	v_mul_f32_e32 v0, v85, v0
	v_cvt_pk_bf16_f32 v1, v1, v144
	ds_write_b16 v68, v1 offset:7472
	v_cvt_pk_bf16_f32 v0, v0, v144
	ds_write_b16 v68, v0 offset:7536
	s_waitcnt lgkmcnt(0)
